# B-attention epilogue: xor-16/xor-32 reduction steps via v_permlane16/32_swap instead of ds_bpermute + lgkmcnt(0) (8 LDS round trips per unit)
# baseline (speedup 1.0000x reference)
; __device__ __forceinline__ unsigned cvt_pk_bf16(float lo, float hi) { unsigned r; asm volatile("v_cvt_pk_bf16_f32 %0, %1, %2" : "=v"(r) : "v"(lo), "v"(hi)); return r; }
; #define LAS __attribute__((address_space(3)))
; template <int DV, int NMAP> ...
;     ...
;     __builtin_amdgcn_s_setprio(0);
;     asm volatile("s_waitcnt lgkmcnt(0)" ::: "memory"); __builtin_amdgcn_s_barrier(); asm volatile("" ::: "memory");
;     ...
;     float inv[2];
; #pragma unroll
;     for (int qb = 0; qb < 2; ++qb) { float l = lsum[qb]; l += __shfl_xor(l, 16); l += __shfl_xor(l, 32); inv[qb] = 1.0f / l; }
;     if (NMAP == 1) {
; #pragma unroll
;         for (int qb = 0; qb < 2; ++qb) { bf16* rowp = O + (size_t)(q0w + 16 * qb + fr) * DM + vrow0 + 4 * fq;
; #pragma unroll
;             for (int db = 0; db < DV / 16; ++db) { const f32x4 v = o[db][qb] * inv[qb]; v2u w; w.x = pg8::cvt_pk_bf16(v[0], v[1]); w.y = pg8::cvt_pk_bf16(v[2], v[3]); *(v2u*)(rowp + 16 * db) = w; } }
;     } else {
;         LAS f32x4* xch = (LAS f32x4*)(lds + qg * 32768);
;         if (mp == 1) {
; #pragma unroll
;             for (int db = 0; db < DV / 16; ++db)
; #pragma unroll
;                 for (int qb = 0; qb < 2; ++qb) xch[(db * 2 + qb) * 64 + lane] = o[db][qb] * (inv[qb] * lam);
.Lbt_exit:
	s_setprio 0
	v_mov_b32_e32 v124, v219
	s_nop 1
	v_permlane16_swap_b32_e32 v219, v124
	s_waitcnt lgkmcnt(0)
	s_barrier
	s_waitcnt lgkmcnt(0)
	v_add_f32_e32 v124, v219, v124
	v_mov_b32_e32 v125, v124
	s_nop 1
	v_permlane32_swap_b32_e32 v124, v125
	s_waitcnt lgkmcnt(0)
	v_add_f32_e32 v124, v124, v125
	v_div_scale_f32 v125, s[4:5], v124, v124, 1.0
	v_rcp_f32_e32 v126, v125
	s_nop 0
	v_fma_f32 v127, -v125, v126, 1.0
	v_fmac_f32_e32 v126, v127, v126
	v_div_scale_f32 v127, vcc, 1.0, v124, 1.0
	v_mul_f32_e32 v128, v127, v126
	v_fma_f32 v129, -v125, v128, v127
	v_fmac_f32_e32 v128, v129, v126
	v_fma_f32 v125, -v125, v128, v127
	v_div_fmas_f32 v125, v125, v126, v128
	v_div_fixup_f32 v130, v125, v124, 1.0
	v_mov_b32_e32 v124, v218
	s_nop 1
	v_permlane16_swap_b32_e32 v218, v124
	s_waitcnt lgkmcnt(0)
	v_add_f32_e32 v124, v218, v124
	v_mov_b32_e32 v125, v124
	s_nop 1
	v_permlane32_swap_b32_e32 v124, v125
	s_waitcnt lgkmcnt(0)
	v_add_f32_e32 v124, v124, v125
	v_div_scale_f32 v125, s[4:5], v124, v124, 1.0
	v_rcp_f32_e32 v126, v125
	s_lshl_b32 s4, s23, 15
	s_add_i32 s4, s4, 0
	s_cmp_eq_u32 s21, 1
	v_fma_f32 v127, -v125, v126, 1.0
	v_fmac_f32_e32 v126, v127, v126
	v_div_scale_f32 v127, vcc, 1.0, v124, 1.0
	v_mul_f32_e32 v128, v127, v126
	v_fma_f32 v129, -v125, v128, v127
	v_fmac_f32_e32 v128, v129, v126
	v_fma_f32 v125, -v125, v128, v127
	v_div_fmas_f32 v125, v125, v126, v128
	v_div_fixup_f32 v128, v125, v124, 1.0
	v_lshl_add_u32 v129, v237, 4, s4
	s_cbranch_scc0 .LBB0_329
	v_mul_f32_e32 v124, v233, v130
	v_pk_mul_f32 v[134:135], v[158:159], v[124:125] op_sel_hi:[1,0]
	v_pk_mul_f32 v[132:133], v[156:157], v[124:125] op_sel_hi:[1,0]
	v_mul_f32_e32 v126, v233, v128
	ds_write_b128 v129, v[132:135]
	v_pk_mul_f32 v[134:135], v[122:123], v[126:127] op_sel_hi:[1,0]
	v_pk_mul_f32 v[132:133], v[120:121], v[126:127] op_sel_hi:[1,0]
	ds_write_b128 v129, v[132:135] offset:1024
	v_pk_mul_f32 v[134:135], v[118:119], v[124:125] op_sel_hi:[1,0]
	v_pk_mul_f32 v[132:133], v[116:117], v[124:125] op_sel_hi:[1,0]
	ds_write_b128 v129, v[132:135] offset:2048
	v_pk_mul_f32 v[134:135], v[114:115], v[126:127] op_sel_hi:[1,0]
	v_pk_mul_f32 v[132:133], v[112:113], v[126:127] op_sel_hi:[1,0]
	ds_write_b128 v129, v[132:135] offset:3072
	v_pk_mul_f32 v[134:135], v[110:111], v[124:125] op_sel_hi:[1,0]
	v_pk_mul_f32 v[132:133], v[108:109], v[124:125] op_sel_hi:[1,0]
	ds_write_b128 v129, v[132:135] offset:4096
	v_pk_mul_f32 v[134:135], v[106:107], v[126:127] op_sel_hi:[1,0]
	v_pk_mul_f32 v[132:133], v[104:105], v[126:127] op_sel_hi:[1,0]
	ds_write_b128 v129, v[132:135] offset:5120
	v_pk_mul_f32 v[134:135], v[102:103], v[124:125] op_sel_hi:[1,0]
	v_pk_mul_f32 v[132:133], v[100:101], v[124:125] op_sel_hi:[1,0]
	ds_write_b128 v129, v[132:135] offset:6144
	v_pk_mul_f32 v[134:135], v[98:99], v[126:127] op_sel_hi:[1,0]
	v_pk_mul_f32 v[132:133], v[96:97], v[126:127] op_sel_hi:[1,0]
	ds_write_b128 v129, v[132:135] offset:7168
	v_pk_mul_f32 v[134:135], v[94:95], v[124:125] op_sel_hi:[1,0]
	v_pk_mul_f32 v[132:133], v[92:93], v[124:125] op_sel_hi:[1,0]
	ds_write_b128 v129, v[132:135] offset:8192
	v_pk_mul_f32 v[134:135], v[90:91], v[126:127] op_sel_hi:[1,0]
	v_pk_mul_f32 v[132:133], v[88:89], v[126:127] op_sel_hi:[1,0]
	ds_write_b128 v129, v[132:135] offset:9216
	v_pk_mul_f32 v[134:135], v[86:87], v[124:125] op_sel_hi:[1,0]
	v_pk_mul_f32 v[132:133], v[84:85], v[124:125] op_sel_hi:[1,0]
	ds_write_b128 v129, v[132:135] offset:10240
	v_pk_mul_f32 v[134:135], v[82:83], v[126:127] op_sel_hi:[1,0]
	v_pk_mul_f32 v[132:133], v[80:81], v[126:127] op_sel_hi:[1,0]
	ds_write_b128 v129, v[132:135] offset:11264
	v_pk_mul_f32 v[134:135], v[78:79], v[124:125] op_sel_hi:[1,0]
	v_pk_mul_f32 v[132:133], v[76:77], v[124:125] op_sel_hi:[1,0]
	ds_write_b128 v129, v[132:135] offset:12288
	v_pk_mul_f32 v[134:135], v[74:75], v[126:127] op_sel_hi:[1,0]
	v_pk_mul_f32 v[132:133], v[72:73], v[126:127] op_sel_hi:[1,0]
	ds_write_b128 v129, v[132:135] offset:13312
	v_pk_mul_f32 v[134:135], v[70:71], v[124:125] op_sel_hi:[1,0]
	v_pk_mul_f32 v[132:133], v[68:69], v[124:125] op_sel_hi:[1,0]
	ds_write_b128 v129, v[132:135] offset:14336
	v_pk_mul_f32 v[134:135], v[66:67], v[126:127] op_sel_hi:[1,0]
	v_pk_mul_f32 v[132:133], v[64:65], v[126:127] op_sel_hi:[1,0]
	ds_write_b128 v129, v[132:135] offset:15360
	v_pk_mul_f32 v[134:135], v[62:63], v[124:125] op_sel_hi:[1,0]
	v_pk_mul_f32 v[132:133], v[60:61], v[124:125] op_sel_hi:[1,0]
	ds_write_b128 v129, v[132:135] offset:16384
	v_pk_mul_f32 v[134:135], v[58:59], v[126:127] op_sel_hi:[1,0]
	v_pk_mul_f32 v[132:133], v[56:57], v[126:127] op_sel_hi:[1,0]
	ds_write_b128 v129, v[132:135] offset:17408
	v_pk_mul_f32 v[134:135], v[54:55], v[124:125] op_sel_hi:[1,0]
	v_pk_mul_f32 v[132:133], v[52:53], v[124:125] op_sel_hi:[1,0]
	ds_write_b128 v129, v[132:135] offset:18432
	v_pk_mul_f32 v[134:135], v[50:51], v[126:127] op_sel_hi:[1,0]
	v_pk_mul_f32 v[132:133], v[48:49], v[126:127] op_sel_hi:[1,0]
	ds_write_b128 v129, v[132:135] offset:19456
	v_pk_mul_f32 v[134:135], v[46:47], v[124:125] op_sel_hi:[1,0]
	v_pk_mul_f32 v[132:133], v[44:45], v[124:125] op_sel_hi:[1,0]
	ds_write_b128 v129, v[132:135] offset:20480
	v_pk_mul_f32 v[134:135], v[42:43], v[126:127] op_sel_hi:[1,0]
	v_pk_mul_f32 v[132:133], v[40:41], v[126:127] op_sel_hi:[1,0]
	ds_write_b128 v129, v[132:135] offset:21504
	v_pk_mul_f32 v[134:135], v[38:39], v[124:125] op_sel_hi:[1,0]
	v_pk_mul_f32 v[132:133], v[36:37], v[124:125] op_sel_hi:[1,0]
	ds_write_b128 v129, v[132:135] offset:22528
	v_pk_mul_f32 v[134:135], v[34:35], v[126:127] op_sel_hi:[1,0]
	v_pk_mul_f32 v[132:133], v[32:33], v[126:127] op_sel_hi:[1,0]
	ds_write_b128 v129, v[132:135] offset:23552
	v_pk_mul_f32 v[134:135], v[30:31], v[124:125] op_sel_hi:[1,0]
	v_pk_mul_f32 v[132:133], v[28:29], v[124:125] op_sel_hi:[1,0]
	ds_write_b128 v129, v[132:135] offset:24576
	v_pk_mul_f32 v[134:135], v[26:27], v[126:127] op_sel_hi:[1,0]
	v_pk_mul_f32 v[132:133], v[24:25], v[126:127] op_sel_hi:[1,0]
	ds_write_b128 v129, v[132:135] offset:25600
	v_pk_mul_f32 v[134:135], v[22:23], v[124:125] op_sel_hi:[1,0]
	v_pk_mul_f32 v[132:133], v[20:21], v[124:125] op_sel_hi:[1,0]
	ds_write_b128 v129, v[132:135] offset:26624
	v_pk_mul_f32 v[134:135], v[14:15], v[126:127] op_sel_hi:[1,0]
	v_pk_mul_f32 v[132:133], v[12:13], v[126:127] op_sel_hi:[1,0]
	ds_write_b128 v129, v[132:135] offset:27648
	v_pk_mul_f32 v[134:135], v[18:19], v[124:125] op_sel_hi:[1,0]
	v_pk_mul_f32 v[132:133], v[16:17], v[124:125] op_sel_hi:[1,0]
	ds_write_b128 v129, v[132:135] offset:28672
	v_pk_mul_f32 v[134:135], v[10:11], v[126:127] op_sel_hi:[1,0]
	v_pk_mul_f32 v[132:133], v[8:9], v[126:127] op_sel_hi:[1,0]
	ds_write_b128 v129, v[132:135] offset:29696
	v_pk_mul_f32 v[134:135], v[6:7], v[124:125] op_sel_hi:[1,0]
	v_pk_mul_f32 v[132:133], v[4:5], v[124:125] op_sel_hi:[1,0]
	ds_write_b128 v129, v[132:135] offset:30720
	v_pk_mul_f32 v[134:135], v[2:3], v[126:127] op_sel_hi:[1,0]
	v_pk_mul_f32 v[132:133], v[0:1], v[126:127] op_sel_hi:[1,0]
	ds_write_b128 v129, v[132:135] offset:31744
; template <int DV, int NMAP> ...
;     ...
;         asm volatile("s_waitcnt lgkmcnt(0)" ::: "memory"); __builtin_amdgcn_s_barrier(); asm volatile("" ::: "memory");
;         if (mp == 0) {
;             float ss[2] = {0.f, 0.f};
; #pragma unroll
;             for (int db = 0; db < DV / 16; ++db)
; #pragma unroll
;                 for (int qb = 0; qb < 2; ++qb) { const f32x4 x = o[db][qb] * inv[qb] - xch[(db * 2 + qb) * 64 + lane]; o[db][qb] = x; ss[qb] += (x[0] * x[0] + x[1] * x[1]) + (x[2] * x[2] + x[3] * x[3]); if (qb == 1 && (db & 1)) asm volatile("" ::: "memory"); }
.LBB0_329:
	s_waitcnt lgkmcnt(0)
	s_barrier
	s_cmpk_gt_u32 s20, 0xff
	v_mov_b64_e32 v[238:239], v[214:215]
	s_cbranch_scc1 .LBB0_297
	ds_read_b128 v[160:163], v129
	ds_read_b128 v[164:167], v129 offset:1024
	ds_read_b128 v[168:171], v129 offset:2048
	ds_read_b128 v[172:175], v129 offset:3072
	ds_read_b128 v[176:179], v129 offset:4096
	ds_read_b128 v[180:183], v129 offset:5120
	ds_read_b128 v[184:187], v129 offset:6144
	ds_read_b128 v[188:191], v129 offset:7168
	ds_read_b128 v[192:195], v129 offset:8192
	ds_read_b128 v[196:199], v129 offset:9216
	ds_read_b128 v[200:203], v129 offset:10240
	ds_read_b128 v[148:151], v129 offset:11264
	v_lshlrev_b32_e32 v204, 3, v236
	s_waitcnt lgkmcnt(11)
	v_xor_b32_e32 v125, 0x80000000, v163
	v_xor_b32_e32 v124, 0x80000000, v162
	v_pk_fma_f32 v[124:125], v[158:159], v[130:131], v[124:125] op_sel_hi:[1,0,1]
	v_pk_fma_f32 v[126:127], v[156:157], v[130:131], v[160:161] op_sel_hi:[1, 0, 1] neg_lo:[0, 0, 1] neg_hi:[0, 0, 1]
	ds_read_b128 v[160:163], v129 offset:12288
	v_pk_mul_f32 v[132:133], v[124:125], v[124:125]
	v_pk_mul_f32 v[134:135], v[126:127], v[126:127]
	s_nop 0
	v_pk_mov_b32 v[136:137], v[134:135], v[132:133] op_sel:[1,0]
	v_mov_b32_e32 v135, v133
	v_pk_add_f32 v[132:133], v[136:137], v[134:135]
	v_pk_add_f32 v[132:133], v[132:133], v[132:133] op_sel:[0,1] op_sel_hi:[1,0]
	s_waitcnt lgkmcnt(11)
	v_xor_b32_e32 v137, 0x80000000, v167
	v_xor_b32_e32 v136, 0x80000000, v166
	v_pk_fma_f32 v[122:123], v[122:123], v[128:129], v[136:137] op_sel_hi:[1,0,1]
	v_pk_fma_f32 v[120:121], v[120:121], v[128:129], v[164:165] op_sel_hi:[1, 0, 1] neg_lo:[0, 0, 1] neg_hi:[0, 0, 1]
	ds_read_b128 v[164:167], v129 offset:13312
	v_pk_mul_f32 v[134:135], v[122:123], v[122:123]
	v_pk_mul_f32 v[136:137], v[120:121], v[120:121]
	s_nop 0
	v_pk_mov_b32 v[138:139], v[136:137], v[134:135] op_sel:[1,0]
	v_mov_b32_e32 v137, v135
	v_pk_add_f32 v[134:135], v[138:139], v[136:137]
	v_pk_add_f32 v[134:135], v[134:135], v[134:135] op_sel:[0,1] op_sel_hi:[1,0]
	s_waitcnt lgkmcnt(11)
	v_xor_b32_e32 v139, 0x80000000, v171
	v_xor_b32_e32 v138, 0x80000000, v170
	v_pk_fma_f32 v[118:119], v[118:119], v[130:131], v[138:139] op_sel_hi:[1,0,1]
	v_pk_fma_f32 v[116:117], v[116:117], v[130:131], v[168:169] op_sel_hi:[1, 0, 1] neg_lo:[0, 0, 1] neg_hi:[0, 0, 1]
	ds_read_b128 v[168:171], v129 offset:14336
	v_pk_mul_f32 v[136:137], v[118:119], v[118:119]
	v_pk_mul_f32 v[138:139], v[116:117], v[116:117]
	s_nop 0
	v_pk_mov_b32 v[140:141], v[138:139], v[136:137] op_sel:[1,0]
	v_mov_b32_e32 v139, v137
	v_pk_add_f32 v[142:143], v[140:141], v[138:139]
	s_waitcnt lgkmcnt(11)
	v_xor_b32_e32 v139, 0x80000000, v175
	v_xor_b32_e32 v138, 0x80000000, v174
	v_pk_fma_f32 v[114:115], v[114:115], v[128:129], v[138:139] op_sel_hi:[1,0,1]
	v_pk_fma_f32 v[112:113], v[112:113], v[128:129], v[172:173] op_sel_hi:[1, 0, 1] neg_lo:[0, 0, 1] neg_hi:[0, 0, 1]
	ds_read_b128 v[172:175], v129 offset:15360
	v_pk_mul_f32 v[136:137], v[114:115], v[114:115]
	v_pk_mul_f32 v[138:139], v[112:113], v[112:113]
	s_nop 0
	v_pk_mov_b32 v[140:141], v[138:139], v[136:137] op_sel:[1,0]
	v_mov_b32_e32 v139, v137
	v_pk_add_f32 v[136:137], v[140:141], v[138:139]
	v_pk_add_f32 v[136:137], v[136:137], v[136:137] op_sel:[0,1] op_sel_hi:[1,0]
	s_waitcnt lgkmcnt(11)
	v_xor_b32_e32 v141, 0x80000000, v179
	v_xor_b32_e32 v140, 0x80000000, v178
	v_pk_fma_f32 v[110:111], v[110:111], v[130:131], v[140:141] op_sel_hi:[1,0,1]
	v_pk_fma_f32 v[108:109], v[108:109], v[130:131], v[176:177] op_sel_hi:[1, 0, 1] neg_lo:[0, 0, 1] neg_hi:[0, 0, 1]
	ds_read_b128 v[176:179], v129 offset:16384
	s_waitcnt lgkmcnt(11)
	v_xor_b32_e32 v141, 0x80000000, v183
	v_xor_b32_e32 v140, 0x80000000, v182
	v_pk_fma_f32 v[106:107], v[106:107], v[128:129], v[140:141] op_sel_hi:[1,0,1]
	v_pk_fma_f32 v[104:105], v[104:105], v[128:129], v[180:181] op_sel_hi:[1, 0, 1] neg_lo:[0, 0, 1] neg_hi:[0, 0, 1]
	ds_read_b128 v[180:183], v129 offset:17408
	s_waitcnt lgkmcnt(11)
	v_xor_b32_e32 v141, 0x80000000, v187
	v_xor_b32_e32 v140, 0x80000000, v186
	v_pk_fma_f32 v[100:101], v[100:101], v[130:131], v[184:185] op_sel_hi:[1, 0, 1] neg_lo:[0, 0, 1] neg_hi:[0, 0, 1]
	ds_read_b128 v[184:187], v129 offset:18432
	v_pk_fma_f32 v[102:103], v[102:103], v[130:131], v[140:141] op_sel_hi:[1,0,1]
	v_mul_f32_e32 v131, v100, v100
	v_mul_f32_e32 v140, v101, v101
	v_pk_add_f32 v[138:139], v[142:143], v[142:143] op_sel:[0,1] op_sel_hi:[1,0]
	v_mov_b32_e32 v133, v131
	v_mov_b32_e32 v139, v140
	v_pk_add_f32 v[132:133], v[132:133], v[138:139]
	v_mul_f32_e32 v138, v109, v109
	v_mul_f32_e32 v141, v102, v102
	v_pk_fma_f32 v[138:139], v[108:109], v[108:109], v[138:139] op_sel_hi:[1,1,0]
	v_mul_f32_e32 v140, v111, v111
	v_mul_f32_e32 v144, v103, v103
	v_mov_b32_e32 v139, v141
	v_pk_fma_f32 v[140:141], v[110:111], v[110:111], v[140:141] op_sel_hi:[1,1,0]
	s_nop 0
	v_mov_b32_e32 v141, v144
	v_pk_add_f32 v[138:139], v[138:139], v[140:141]
	s_nop 0
	v_pk_add_f32 v[132:133], v[132:133], v[138:139]
	v_pk_add_f32 v[132:133], v[132:133], v[132:133] op_sel:[0,1] op_sel_hi:[1,0]
	s_waitcnt lgkmcnt(11)
	v_pk_fma_f32 v[96:97], v[96:97], v[128:129], v[188:189] op_sel_hi:[1, 0, 1] neg_lo:[0, 0, 1] neg_hi:[0, 0, 1]
	s_nop 0
	v_mul_f32_e32 v131, v96, v96
	v_mul_f32_e32 v138, v97, v97
	v_xor_b32_e32 v141, 0x80000000, v191
	v_xor_b32_e32 v140, 0x80000000, v190
	ds_read_b128 v[188:191], v129 offset:19456
	v_mov_b32_e32 v135, v131
	v_mov_b32_e32 v137, v138
	v_pk_fma_f32 v[98:99], v[98:99], v[128:129], v[140:141] op_sel_hi:[1,0,1]
	v_pk_add_f32 v[134:135], v[134:135], v[136:137]
	v_mul_f32_e32 v136, v105, v105
	v_mul_f32_e32 v139, v98, v98
	v_pk_fma_f32 v[136:137], v[104:105], v[104:105], v[136:137] op_sel_hi:[1,1,0]
	v_mul_f32_e32 v138, v107, v107
	v_mul_f32_e32 v140, v99, v99
	v_mov_b32_e32 v137, v139
	v_pk_fma_f32 v[138:139], v[106:107], v[106:107], v[138:139] op_sel_hi:[1,1,0]
	s_nop 0
	v_mov_b32_e32 v139, v140
	v_pk_add_f32 v[136:137], v[136:137], v[138:139]
	s_nop 0
	v_pk_add_f32 v[134:135], v[134:135], v[136:137]
	v_pk_add_f32 v[134:135], v[134:135], v[134:135] op_sel:[0,1] op_sel_hi:[1,0]
	s_waitcnt lgkmcnt(11)
; template <int DV, int NMAP> ...
;     ...
; #pragma unroll
;             for (int db = 0; db < DV / 16; ++db)
; #pragma unroll
;                 for (int qb = 0; qb < 2; ++qb) { const f32x4 x = o[db][qb] * inv[qb] - xch[(db * 2 + qb) * 64 + lane]; o[db][qb] = x; ss[qb] += (x[0] * x[0] + x[1] * x[1]) + (x[2] * x[2] + x[3] * x[3]); if (qb == 1 && (db & 1)) asm volatile("" ::: "memory"); }
	v_xor_b32_e32 v139, 0x80000000, v195
	v_xor_b32_e32 v138, 0x80000000, v194
	v_pk_fma_f32 v[94:95], v[94:95], v[130:131], v[138:139] op_sel_hi:[1,0,1]
	v_pk_fma_f32 v[92:93], v[92:93], v[130:131], v[192:193] op_sel_hi:[1, 0, 1] neg_lo:[0, 0, 1] neg_hi:[0, 0, 1]
	ds_read_b128 v[192:195], v129 offset:20480
	v_pk_mul_f32 v[136:137], v[94:95], v[94:95]
	v_pk_mul_f32 v[138:139], v[92:93], v[92:93]
	s_nop 0
	v_pk_mov_b32 v[140:141], v[138:139], v[136:137] op_sel:[1,0]
	v_mov_b32_e32 v139, v137
	v_pk_add_f32 v[142:143], v[140:141], v[138:139]
	s_waitcnt lgkmcnt(11)
	v_xor_b32_e32 v139, 0x80000000, v199
	v_xor_b32_e32 v138, 0x80000000, v198
	v_pk_fma_f32 v[90:91], v[90:91], v[128:129], v[138:139] op_sel_hi:[1,0,1]
	v_pk_fma_f32 v[88:89], v[88:89], v[128:129], v[196:197] op_sel_hi:[1, 0, 1] neg_lo:[0, 0, 1] neg_hi:[0, 0, 1]
	ds_read_b128 v[196:199], v129 offset:21504
	v_pk_mul_f32 v[136:137], v[90:91], v[90:91]
	v_pk_mul_f32 v[138:139], v[88:89], v[88:89]
	s_nop 0
	v_pk_mov_b32 v[140:141], v[138:139], v[136:137] op_sel:[1,0]
	v_mov_b32_e32 v139, v137
	v_pk_add_f32 v[136:137], v[140:141], v[138:139]
	v_pk_add_f32 v[136:137], v[136:137], v[136:137] op_sel:[0,1] op_sel_hi:[1,0]
	s_waitcnt lgkmcnt(11)
	v_xor_b32_e32 v141, 0x80000000, v203
	v_xor_b32_e32 v140, 0x80000000, v202
	v_pk_fma_f32 v[86:87], v[86:87], v[130:131], v[140:141] op_sel_hi:[1,0,1]
	v_pk_fma_f32 v[84:85], v[84:85], v[130:131], v[200:201] op_sel_hi:[1, 0, 1] neg_lo:[0, 0, 1] neg_hi:[0, 0, 1]
	ds_read_b128 v[200:203], v129 offset:22528
	s_waitcnt lgkmcnt(11)
	v_xor_b32_e32 v141, 0x80000000, v151
	v_xor_b32_e32 v140, 0x80000000, v150
	v_pk_fma_f32 v[82:83], v[82:83], v[128:129], v[140:141] op_sel_hi:[1,0,1]
	v_pk_fma_f32 v[80:81], v[80:81], v[128:129], v[148:149] op_sel_hi:[1, 0, 1] neg_lo:[0, 0, 1] neg_hi:[0, 0, 1]
	ds_read_b128 v[148:151], v129 offset:23552
	s_waitcnt lgkmcnt(11)
	v_xor_b32_e32 v141, 0x80000000, v163
	v_xor_b32_e32 v140, 0x80000000, v162
	v_pk_fma_f32 v[76:77], v[76:77], v[130:131], v[160:161] op_sel_hi:[1, 0, 1] neg_lo:[0, 0, 1] neg_hi:[0, 0, 1]
	ds_read_b128 v[160:163], v129 offset:24576
	v_pk_fma_f32 v[78:79], v[78:79], v[130:131], v[140:141] op_sel_hi:[1,0,1]
	v_mul_f32_e32 v131, v76, v76
	v_mul_f32_e32 v140, v77, v77
	v_pk_add_f32 v[138:139], v[142:143], v[142:143] op_sel:[0,1] op_sel_hi:[1,0]
	v_mov_b32_e32 v133, v131
	v_mov_b32_e32 v139, v140
	v_pk_add_f32 v[132:133], v[132:133], v[138:139]
	v_mul_f32_e32 v138, v85, v85
	v_mul_f32_e32 v141, v78, v78
	v_pk_fma_f32 v[138:139], v[84:85], v[84:85], v[138:139] op_sel_hi:[1,1,0]
	v_mul_f32_e32 v140, v87, v87
	v_mul_f32_e32 v144, v79, v79
	v_mov_b32_e32 v139, v141
	v_pk_fma_f32 v[140:141], v[86:87], v[86:87], v[140:141] op_sel_hi:[1,1,0]
	s_nop 0
	v_mov_b32_e32 v141, v144
	v_pk_add_f32 v[138:139], v[138:139], v[140:141]
	s_nop 0
	v_pk_add_f32 v[132:133], v[132:133], v[138:139]
	v_pk_add_f32 v[132:133], v[132:133], v[132:133] op_sel:[0,1] op_sel_hi:[1,0]
	s_waitcnt lgkmcnt(11)
	v_pk_fma_f32 v[72:73], v[72:73], v[128:129], v[164:165] op_sel_hi:[1, 0, 1] neg_lo:[0, 0, 1] neg_hi:[0, 0, 1]
	s_nop 0
	v_mul_f32_e32 v131, v72, v72
	v_mul_f32_e32 v138, v73, v73
	v_xor_b32_e32 v141, 0x80000000, v167
	v_xor_b32_e32 v140, 0x80000000, v166
	ds_read_b128 v[164:167], v129 offset:25600
	v_mov_b32_e32 v135, v131
	v_mov_b32_e32 v137, v138
	v_pk_fma_f32 v[74:75], v[74:75], v[128:129], v[140:141] op_sel_hi:[1,0,1]
	v_pk_add_f32 v[134:135], v[134:135], v[136:137]
	v_mul_f32_e32 v136, v81, v81
	v_mul_f32_e32 v139, v74, v74
	v_pk_fma_f32 v[136:137], v[80:81], v[80:81], v[136:137] op_sel_hi:[1,1,0]
	v_mul_f32_e32 v138, v83, v83
	v_mul_f32_e32 v140, v75, v75
	v_mov_b32_e32 v137, v139
	v_pk_fma_f32 v[138:139], v[82:83], v[82:83], v[138:139] op_sel_hi:[1,1,0]
	s_nop 0
	v_mov_b32_e32 v139, v140
	v_pk_add_f32 v[136:137], v[136:137], v[138:139]
	s_nop 0
	v_pk_add_f32 v[134:135], v[134:135], v[136:137]
	v_pk_add_f32 v[134:135], v[134:135], v[134:135] op_sel:[0,1] op_sel_hi:[1,0]
	s_waitcnt lgkmcnt(11)
	v_xor_b32_e32 v139, 0x80000000, v171
	v_xor_b32_e32 v138, 0x80000000, v170
	v_pk_fma_f32 v[70:71], v[70:71], v[130:131], v[138:139] op_sel_hi:[1,0,1]
	v_pk_fma_f32 v[68:69], v[68:69], v[130:131], v[168:169] op_sel_hi:[1, 0, 1] neg_lo:[0, 0, 1] neg_hi:[0, 0, 1]
	ds_read_b128 v[168:171], v129 offset:26624
	v_pk_mul_f32 v[136:137], v[70:71], v[70:71]
	v_pk_mul_f32 v[138:139], v[68:69], v[68:69]
	s_nop 0
	v_pk_mov_b32 v[140:141], v[138:139], v[136:137] op_sel:[1,0]
	v_mov_b32_e32 v139, v137
	v_pk_add_f32 v[142:143], v[140:141], v[138:139]
	s_waitcnt lgkmcnt(11)
	v_xor_b32_e32 v139, 0x80000000, v175
	v_xor_b32_e32 v138, 0x80000000, v174
	v_pk_fma_f32 v[66:67], v[66:67], v[128:129], v[138:139] op_sel_hi:[1,0,1]
	v_pk_fma_f32 v[64:65], v[64:65], v[128:129], v[172:173] op_sel_hi:[1, 0, 1] neg_lo:[0, 0, 1] neg_hi:[0, 0, 1]
	ds_read_b128 v[172:175], v129 offset:27648
	v_pk_mul_f32 v[136:137], v[66:67], v[66:67]
	v_pk_mul_f32 v[138:139], v[64:65], v[64:65]
	s_nop 0
	v_pk_mov_b32 v[140:141], v[138:139], v[136:137] op_sel:[1,0]
	v_mov_b32_e32 v139, v137
	v_pk_add_f32 v[136:137], v[140:141], v[138:139]
	v_pk_add_f32 v[136:137], v[136:137], v[136:137] op_sel:[0,1] op_sel_hi:[1,0]
	s_waitcnt lgkmcnt(11)
	v_xor_b32_e32 v141, 0x80000000, v179
	v_xor_b32_e32 v140, 0x80000000, v178
	v_pk_fma_f32 v[62:63], v[62:63], v[130:131], v[140:141] op_sel_hi:[1,0,1]
	v_pk_fma_f32 v[60:61], v[60:61], v[130:131], v[176:177] op_sel_hi:[1, 0, 1] neg_lo:[0, 0, 1] neg_hi:[0, 0, 1]
	ds_read_b128 v[176:179], v129 offset:28672
	s_waitcnt lgkmcnt(11)
; template <int DV, int NMAP> ...
;     ...
; #pragma unroll
;             for (int db = 0; db < DV / 16; ++db)
; #pragma unroll
;                 for (int qb = 0; qb < 2; ++qb) { const f32x4 x = o[db][qb] * inv[qb] - xch[(db * 2 + qb) * 64 + lane]; o[db][qb] = x; ss[qb] += (x[0] * x[0] + x[1] * x[1]) + (x[2] * x[2] + x[3] * x[3]); if (qb == 1 && (db & 1)) asm volatile("" ::: "memory"); }
	v_xor_b32_e32 v141, 0x80000000, v183
	v_xor_b32_e32 v140, 0x80000000, v182
	v_pk_fma_f32 v[58:59], v[58:59], v[128:129], v[140:141] op_sel_hi:[1,0,1]
	v_pk_fma_f32 v[56:57], v[56:57], v[128:129], v[180:181] op_sel_hi:[1, 0, 1] neg_lo:[0, 0, 1] neg_hi:[0, 0, 1]
	ds_read_b128 v[180:183], v129 offset:29696
	s_waitcnt lgkmcnt(11)
	v_xor_b32_e32 v141, 0x80000000, v187
	v_xor_b32_e32 v140, 0x80000000, v186
	v_pk_fma_f32 v[52:53], v[52:53], v[130:131], v[184:185] op_sel_hi:[1, 0, 1] neg_lo:[0, 0, 1] neg_hi:[0, 0, 1]
	ds_read_b128 v[184:187], v129 offset:30720
	v_pk_fma_f32 v[54:55], v[54:55], v[130:131], v[140:141] op_sel_hi:[1,0,1]
	v_mul_f32_e32 v131, v52, v52
	v_mul_f32_e32 v140, v53, v53
	v_pk_add_f32 v[138:139], v[142:143], v[142:143] op_sel:[0,1] op_sel_hi:[1,0]
	v_mov_b32_e32 v133, v131
	v_mov_b32_e32 v139, v140
	v_pk_add_f32 v[132:133], v[132:133], v[138:139]
	v_mul_f32_e32 v138, v61, v61
	v_mul_f32_e32 v141, v54, v54
	v_pk_fma_f32 v[138:139], v[60:61], v[60:61], v[138:139] op_sel_hi:[1,1,0]
	v_mul_f32_e32 v140, v63, v63
	v_mul_f32_e32 v144, v55, v55
	v_mov_b32_e32 v139, v141
	v_pk_fma_f32 v[140:141], v[62:63], v[62:63], v[140:141] op_sel_hi:[1,1,0]
	s_nop 0
	v_mov_b32_e32 v141, v144
	v_pk_add_f32 v[138:139], v[138:139], v[140:141]
	s_nop 0
	v_pk_add_f32 v[132:133], v[132:133], v[138:139]
	v_pk_add_f32 v[132:133], v[132:133], v[132:133] op_sel:[0,1] op_sel_hi:[1,0]
	s_waitcnt lgkmcnt(11)
	v_pk_fma_f32 v[48:49], v[48:49], v[128:129], v[188:189] op_sel_hi:[1, 0, 1] neg_lo:[0, 0, 1] neg_hi:[0, 0, 1]
	s_nop 0
	v_mul_f32_e32 v131, v48, v48
	v_mul_f32_e32 v138, v49, v49
	v_xor_b32_e32 v141, 0x80000000, v191
	v_xor_b32_e32 v140, 0x80000000, v190
	ds_read_b128 v[188:191], v129 offset:31744
	v_mov_b32_e32 v135, v131
	v_mov_b32_e32 v137, v138
	v_pk_fma_f32 v[50:51], v[50:51], v[128:129], v[140:141] op_sel_hi:[1,0,1]
	v_pk_add_f32 v[134:135], v[134:135], v[136:137]
	v_mul_f32_e32 v136, v57, v57
	v_mul_f32_e32 v139, v50, v50
	v_pk_fma_f32 v[136:137], v[56:57], v[56:57], v[136:137] op_sel_hi:[1,1,0]
	v_mul_f32_e32 v138, v59, v59
	v_mul_f32_e32 v140, v51, v51
	v_mov_b32_e32 v137, v139
	v_pk_fma_f32 v[138:139], v[58:59], v[58:59], v[138:139] op_sel_hi:[1,1,0]
	s_nop 0
	v_mov_b32_e32 v139, v140
	v_pk_add_f32 v[136:137], v[136:137], v[138:139]
	s_nop 0
	v_pk_add_f32 v[134:135], v[134:135], v[136:137]
	s_waitcnt lgkmcnt(11)
	v_xor_b32_e32 v139, 0x80000000, v195
	v_xor_b32_e32 v138, 0x80000000, v194
	v_pk_fma_f32 v[46:47], v[46:47], v[130:131], v[138:139] op_sel_hi:[1,0,1]
	v_pk_fma_f32 v[44:45], v[44:45], v[130:131], v[192:193] op_sel_hi:[1, 0, 1] neg_lo:[0, 0, 1] neg_hi:[0, 0, 1]
	v_pk_mul_f32 v[136:137], v[46:47], v[46:47]
	v_pk_mul_f32 v[138:139], v[44:45], v[44:45]
	s_nop 0
	v_pk_mov_b32 v[140:141], v[138:139], v[136:137] op_sel:[1,0]
	v_mov_b32_e32 v139, v137
	v_pk_add_f32 v[142:143], v[140:141], v[138:139]
	s_waitcnt lgkmcnt(10)
	v_xor_b32_e32 v139, 0x80000000, v199
	v_xor_b32_e32 v138, 0x80000000, v198
	v_pk_fma_f32 v[42:43], v[42:43], v[128:129], v[138:139] op_sel_hi:[1,0,1]
	v_pk_fma_f32 v[40:41], v[40:41], v[128:129], v[196:197] op_sel_hi:[1, 0, 1] neg_lo:[0, 0, 1] neg_hi:[0, 0, 1]
	v_pk_mul_f32 v[136:137], v[42:43], v[42:43]
	v_pk_mul_f32 v[138:139], v[40:41], v[40:41]
	s_nop 0
	v_pk_mov_b32 v[140:141], v[138:139], v[136:137] op_sel:[1,0]
	v_mov_b32_e32 v139, v137
	v_pk_add_f32 v[136:137], v[140:141], v[138:139]
	s_waitcnt lgkmcnt(9)
	v_xor_b32_e32 v141, 0x80000000, v203
	v_xor_b32_e32 v140, 0x80000000, v202
	v_pk_fma_f32 v[38:39], v[38:39], v[130:131], v[140:141] op_sel_hi:[1,0,1]
	v_pk_fma_f32 v[36:37], v[36:37], v[130:131], v[200:201] op_sel_hi:[1, 0, 1] neg_lo:[0, 0, 1] neg_hi:[0, 0, 1]
	s_waitcnt lgkmcnt(8)
	v_xor_b32_e32 v141, 0x80000000, v151
	v_xor_b32_e32 v140, 0x80000000, v150
	v_pk_fma_f32 v[34:35], v[34:35], v[128:129], v[140:141] op_sel_hi:[1,0,1]
	v_pk_fma_f32 v[32:33], v[32:33], v[128:129], v[148:149] op_sel_hi:[1, 0, 1] neg_lo:[0, 0, 1] neg_hi:[0, 0, 1]
	s_waitcnt lgkmcnt(7)
	v_xor_b32_e32 v141, 0x80000000, v163
	v_xor_b32_e32 v140, 0x80000000, v162
	v_pk_fma_f32 v[28:29], v[28:29], v[130:131], v[160:161] op_sel_hi:[1, 0, 1] neg_lo:[0, 0, 1] neg_hi:[0, 0, 1]
	v_pk_fma_f32 v[30:31], v[30:31], v[130:131], v[140:141] op_sel_hi:[1,0,1]
	v_mul_f32_e32 v131, v28, v28
	v_mul_f32_e32 v140, v29, v29
	v_pk_add_f32 v[138:139], v[142:143], v[142:143] op_sel:[0,1] op_sel_hi:[1,0]
	v_mov_b32_e32 v133, v131
	v_mov_b32_e32 v139, v140
	v_pk_add_f32 v[132:133], v[132:133], v[138:139]
	v_mul_f32_e32 v138, v37, v37
	v_mul_f32_e32 v141, v30, v30
	v_pk_fma_f32 v[138:139], v[36:37], v[36:37], v[138:139] op_sel_hi:[1,1,0]
	v_mul_f32_e32 v140, v39, v39
	v_mul_f32_e32 v144, v31, v31
	v_mov_b32_e32 v139, v141
	v_pk_fma_f32 v[140:141], v[38:39], v[38:39], v[140:141] op_sel_hi:[1,1,0]
	s_nop 0
	v_mov_b32_e32 v141, v144
	v_pk_add_f32 v[138:139], v[138:139], v[140:141]
	v_pk_add_f32 v[138:139], v[132:133], v[138:139]
	s_waitcnt lgkmcnt(6)
	v_xor_b32_e32 v133, 0x80000000, v167
	v_xor_b32_e32 v132, 0x80000000, v166
	v_pk_fma_f32 v[24:25], v[24:25], v[128:129], v[164:165] op_sel_hi:[1, 0, 1] neg_lo:[0, 0, 1] neg_hi:[0, 0, 1]
	v_pk_fma_f32 v[26:27], v[26:27], v[128:129], v[132:133] op_sel_hi:[1,0,1]
	v_mul_f32_e32 v131, v24, v24
	v_mul_f32_e32 v140, v25, v25
	v_pk_add_f32 v[132:133], v[134:135], v[134:135] op_sel:[0,1] op_sel_hi:[1,0]
	v_pk_add_f32 v[134:135], v[136:137], v[136:137] op_sel:[0,1] op_sel_hi:[1,0]
	v_mov_b32_e32 v133, v131
	v_mov_b32_e32 v135, v140
	v_pk_add_f32 v[132:133], v[132:133], v[134:135]
	v_mul_f32_e32 v134, v33, v33
	v_mul_f32_e32 v136, v35, v35
	v_mul_f32_e32 v141, v26, v26
	v_mul_f32_e32 v142, v27, v27
	v_pk_fma_f32 v[134:135], v[32:33], v[32:33], v[134:135] op_sel_hi:[1,1,0]
	v_pk_fma_f32 v[136:137], v[34:35], v[34:35], v[136:137] op_sel_hi:[1,1,0]
	v_mov_b32_e32 v135, v141
	v_mov_b32_e32 v137, v142
	v_pk_add_f32 v[134:135], v[134:135], v[136:137]
	s_nop 0
	v_pk_add_f32 v[136:137], v[132:133], v[134:135]
	s_waitcnt lgkmcnt(5)
; template <int DV, int NMAP> ...
;     ...
;                 for (int qb = 0; qb < 2; ++qb) { const f32x4 x = o[db][qb] * inv[qb] - xch[(db * 2 + qb) * 64 + lane]; o[db][qb] = x; ss[qb] += (x[0] * x[0] + x[1] * x[1]) + (x[2] * x[2] + x[3] * x[3]); if (qb == 1 && (db & 1)) asm volatile("" ::: "memory"); }
; #pragma unroll
;             for (int qb = 0; qb < 2; ++qb) { float v = ss[qb]; v += __shfl_xor(v, 16); v += __shfl_xor(v, 32); ss[qb] = outscale / sqrtf(v * (1.0f / DV) + RMS_EPS); }
; #pragma unroll
;             for (int db = 0; db < DV / 16; ++db) { const f32x4 g = *(const f32x4*)(subg + 16 * db + 4 * fq);
	v_xor_b32_e32 v135, 0x80000000, v171
	v_xor_b32_e32 v134, 0x80000000, v170
	v_pk_fma_f32 v[22:23], v[22:23], v[130:131], v[134:135] op_sel_hi:[1,0,1]
	v_pk_fma_f32 v[20:21], v[20:21], v[130:131], v[168:169] op_sel_hi:[1, 0, 1] neg_lo:[0, 0, 1] neg_hi:[0, 0, 1]
	v_pk_mul_f32 v[132:133], v[22:23], v[22:23]
	v_pk_mul_f32 v[134:135], v[20:21], v[20:21]
	s_nop 0
	v_pk_mov_b32 v[140:141], v[134:135], v[132:133] op_sel:[1,0]
	v_mov_b32_e32 v135, v133
	v_pk_add_f32 v[146:147], v[140:141], v[134:135]
	s_waitcnt lgkmcnt(4)
	v_xor_b32_e32 v133, 0x80000000, v175
	v_xor_b32_e32 v132, 0x80000000, v174
	v_pk_fma_f32 v[132:133], v[14:15], v[128:129], v[132:133] op_sel_hi:[1,0,1]
	v_pk_fma_f32 v[134:135], v[12:13], v[128:129], v[172:173] op_sel_hi:[1, 0, 1] neg_lo:[0, 0, 1] neg_hi:[0, 0, 1]
	v_pk_mul_f32 v[12:13], v[132:133], v[132:133]
	v_pk_mul_f32 v[14:15], v[134:135], v[134:135]
	s_nop 0
	v_pk_mov_b32 v[140:141], v[14:15], v[12:13] op_sel:[1,0]
	v_mov_b32_e32 v15, v13
	s_waitcnt lgkmcnt(3)
	v_xor_b32_e32 v13, 0x80000000, v179
	v_xor_b32_e32 v12, 0x80000000, v178
	v_pk_add_f32 v[140:141], v[140:141], v[14:15]
	v_pk_fma_f32 v[12:13], v[18:19], v[130:131], v[12:13] op_sel_hi:[1,0,1]
	v_pk_fma_f32 v[14:15], v[16:17], v[130:131], v[176:177] op_sel_hi:[1, 0, 1] neg_lo:[0, 0, 1] neg_hi:[0, 0, 1]
	s_waitcnt lgkmcnt(2)
	v_xor_b32_e32 v19, 0x80000000, v183
	v_xor_b32_e32 v18, 0x80000000, v182
	v_pk_fma_f32 v[10:11], v[10:11], v[128:129], v[18:19] op_sel_hi:[1,0,1]
	v_pk_fma_f32 v[8:9], v[8:9], v[128:129], v[180:181] op_sel_hi:[1, 0, 1] neg_lo:[0, 0, 1] neg_hi:[0, 0, 1]
	s_waitcnt lgkmcnt(1)
	v_xor_b32_e32 v19, 0x80000000, v187
	v_xor_b32_e32 v18, 0x80000000, v186
	v_pk_fma_f32 v[4:5], v[4:5], v[130:131], v[184:185] op_sel_hi:[1, 0, 1] neg_lo:[0, 0, 1] neg_hi:[0, 0, 1]
	v_pk_fma_f32 v[6:7], v[6:7], v[130:131], v[18:19] op_sel_hi:[1,0,1]
	v_mul_f32_e32 v18, v4, v4
	v_pk_add_f32 v[16:17], v[138:139], v[138:139] op_sel:[0,1] op_sel_hi:[1,0]
	v_mul_f32_e32 v130, v5, v5
	v_mov_b32_e32 v17, v18
	v_pk_add_f32 v[18:19], v[146:147], v[146:147] op_sel:[0,1] op_sel_hi:[1,0]
	v_mul_f32_e32 v131, v6, v6
	v_mov_b32_e32 v19, v130
	v_pk_add_f32 v[16:17], v[16:17], v[18:19]
	v_mul_f32_e32 v18, v15, v15
	v_pk_fma_f32 v[18:19], v[14:15], v[14:15], v[18:19] op_sel_hi:[1,1,0]
	v_mul_f32_e32 v130, v13, v13
	v_mul_f32_e32 v142, v7, v7
	v_mov_b32_e32 v19, v131
	v_pk_fma_f32 v[130:131], v[12:13], v[12:13], v[130:131] op_sel_hi:[1,1,0]
	s_nop 0
	v_mov_b32_e32 v131, v142
	v_pk_add_f32 v[18:19], v[18:19], v[130:131]
	s_nop 0
	v_pk_add_f32 v[16:17], v[16:17], v[18:19]
	s_waitcnt lgkmcnt(0)
	v_pk_fma_f32 v[18:19], v[0:1], v[128:129], v[188:189] op_sel_hi:[1, 0, 1] neg_lo:[0, 0, 1] neg_hi:[0, 0, 1]
	v_add_f32_e32 v130, v16, v17
	v_xor_b32_e32 v17, 0x80000000, v191
	v_xor_b32_e32 v16, 0x80000000, v190
	v_lshlrev_b32_e32 v206, 4, v236
	global_load_dwordx4 v[160:163], v206, s[46:47]
	global_load_dwordx4 v[164:167], v206, s[46:47] offset:64
	global_load_dwordx4 v[168:171], v206, s[46:47] offset:128
	global_load_dwordx4 v[172:175], v206, s[46:47] offset:192
	global_load_dwordx4 v[176:179], v206, s[46:47] offset:256
	global_load_dwordx4 v[180:183], v206, s[46:47] offset:320
	global_load_dwordx4 v[184:187], v206, s[46:47] offset:384
	global_load_dwordx4 v[188:191], v206, s[46:47] offset:448
	global_load_dwordx4 v[192:195], v206, s[46:47] offset:512
	global_load_dwordx4 v[196:199], v206, s[46:47] offset:576
	global_load_dwordx4 v[200:203], v206, s[46:47] offset:640
	global_load_dwordx4 v[148:151], v206, s[46:47] offset:704
	global_load_dwordx4 v[152:155], v206, s[46:47] offset:768
	global_load_dwordx4 v[240:243], v206, s[46:47] offset:832
	global_load_dwordx4 v[244:247], v206, s[46:47] offset:896
	global_load_dwordx4 v[248:251], v206, s[46:47] offset:960
	v_pk_fma_f32 v[16:17], v[2:3], v[128:129], v[16:17] op_sel_hi:[1,0,1]
	v_mul_f32_e32 v2, v18, v18
	v_pk_add_f32 v[0:1], v[136:137], v[136:137] op_sel:[0,1] op_sel_hi:[1,0]
	v_mul_f32_e32 v128, v19, v19
	v_mov_b32_e32 v1, v2
	v_pk_add_f32 v[2:3], v[140:141], v[140:141] op_sel:[0,1] op_sel_hi:[1,0]
	v_mul_f32_e32 v129, v16, v16
	v_mov_b32_e32 v3, v128
	v_pk_add_f32 v[0:1], v[0:1], v[2:3]
	v_mul_f32_e32 v2, v9, v9
	v_pk_fma_f32 v[2:3], v[8:9], v[8:9], v[2:3] op_sel_hi:[1,1,0]
	v_mul_f32_e32 v128, v11, v11
	v_mul_f32_e32 v131, v17, v17
	v_mov_b32_e32 v3, v129
	v_pk_fma_f32 v[128:129], v[10:11], v[10:11], v[128:129] op_sel_hi:[1,1,0]
	s_nop 0
	v_mov_b32_e32 v129, v131
	v_pk_add_f32 v[2:3], v[2:3], v[128:129]
	s_nop 0
	v_pk_add_f32 v[0:1], v[0:1], v[2:3]
	s_nop 0
	v_add_f32_e32 v0, v0, v1
	v_mov_b32_e32 v1, v130
	s_nop 1
	v_permlane16_swap_b32_e32 v130, v1
	s_waitcnt lgkmcnt(0)
	v_add_f32_e32 v1, v130, v1
	v_mov_b32_e32 v2, v1
	s_nop 1
	v_permlane32_swap_b32_e32 v1, v2
	s_waitcnt lgkmcnt(0)
	v_add_f32_e32 v1, v1, v2
	v_fmamk_f32 v1, v1, 0x3b800000, v226
	v_cmp_gt_f32_e32 vcc, s93, v1
	v_mul_f32_e32 v2, 0x4f800000, v1
	s_nop 0
	v_cndmask_b32_e32 v1, v1, v2, vcc
	v_sqrt_f32_e32 v2, v1
	s_nop 0
	v_add_u32_e32 v3, -1, v2
	v_fma_f32 v128, -v3, v2, v1
	v_cmp_ge_f32_e64 s[38:39], 0, v128
	v_add_u32_e32 v128, 1, v2
	s_nop 0
	v_cndmask_b32_e64 v3, v2, v3, s[38:39]
	v_fma_f32 v2, -v128, v2, v1
	v_cmp_lt_f32_e64 s[38:39], 0, v2
	s_nop 1
	v_cndmask_b32_e64 v2, v3, v128, s[38:39]
	v_mul_f32_e32 v3, 0x37800000, v2
	v_cndmask_b32_e32 v2, v2, v3, vcc
	v_cmp_class_f32_e32 vcc, v1, v227
	s_nop 1
	v_cndmask_b32_e32 v1, v2, v1, vcc
	v_div_scale_f32 v2, s[4:5], v1, v1, v234
	v_rcp_f32_e32 v3, v2
	s_nop 0
	v_fma_f32 v128, -v2, v3, 1.0
	v_fmac_f32_e32 v3, v128, v3
	v_div_scale_f32 v128, vcc, v234, v1, v234
	v_mul_f32_e32 v129, v128, v3
	v_fma_f32 v130, -v2, v129, v128
	v_fmac_f32_e32 v129, v130, v3
	v_fma_f32 v2, -v2, v129, v128
	v_div_fmas_f32 v2, v2, v3, v129
	v_div_fixup_f32 v130, v2, v1, v234
	v_mov_b32_e32 v1, v0
	s_nop 1
	v_permlane16_swap_b32_e32 v0, v1
	s_waitcnt lgkmcnt(0)
; __device__ __forceinline__ unsigned cvt_pk_bf16(float lo, float hi) { unsigned r; asm volatile("v_cvt_pk_bf16_f32 %0, %1, %2" : "=v"(r) : "v"(lo), "v"(hi)); return r; }
; template <int DV, int NMAP> ...
;     ...
;             for (int qb = 0; qb < 2; ++qb) { float v = ss[qb]; v += __shfl_xor(v, 16); v += __shfl_xor(v, 32); ss[qb] = outscale / sqrtf(v * (1.0f / DV) + RMS_EPS); }
; #pragma unroll
;             for (int db = 0; db < DV / 16; ++db) { const f32x4 g = *(const f32x4*)(subg + 16 * db + 4 * fq);
; #pragma unroll
;                 for (int qb = 0; qb < 2; ++qb) { const f32x4 v = o[db][qb] * g * ss[qb]; v2u w; w.x = pg8::cvt_pk_bf16(v[0], v[1]); w.y = pg8::cvt_pk_bf16(v[2], v[3]);
;                     *(v2u*)(O + (size_t)(q0w + 16 * qb + fr) * DM + vrow0 + 16 * db + 4 * fq) = w; } }
	v_add_f32_e32 v0, v0, v1
	v_mov_b32_e32 v1, v0
	s_nop 1
	v_permlane32_swap_b32_e32 v0, v1
	s_waitcnt lgkmcnt(0)
	v_add_f32_e32 v0, v0, v1
	v_fmamk_f32 v0, v0, 0x3b800000, v226
	v_cmp_gt_f32_e32 vcc, s93, v0
	v_mul_f32_e32 v1, 0x4f800000, v0
	s_nop 0
	v_cndmask_b32_e32 v0, v0, v1, vcc
	v_sqrt_f32_e32 v1, v0
	s_nop 0
	v_add_u32_e32 v2, -1, v1
	v_fma_f32 v3, -v2, v1, v0
	v_cmp_ge_f32_e64 s[38:39], 0, v3
	v_add_u32_e32 v3, 1, v1
	s_nop 0
	v_cndmask_b32_e64 v2, v1, v2, s[38:39]
	v_fma_f32 v1, -v3, v1, v0
	v_cmp_lt_f32_e64 s[38:39], 0, v1
	s_nop 1
	v_cndmask_b32_e64 v1, v2, v3, s[38:39]
	v_mul_f32_e32 v2, 0x37800000, v1
	v_cndmask_b32_e32 v1, v1, v2, vcc
	v_cmp_class_f32_e32 vcc, v0, v227
	s_nop 1
	v_cndmask_b32_e32 v0, v1, v0, vcc
	v_div_scale_f32 v1, s[4:5], v0, v0, v234
	v_rcp_f32_e32 v2, v1
	s_lshl_b32 s4, s36, 1
	s_add_u32 s4, s98, s4
	s_addc_u32 s5, s99, 0
	v_fma_f32 v3, -v1, v2, 1.0
	v_fmac_f32_e32 v2, v3, v2
	v_div_scale_f32 v3, vcc, v234, v0, v234
	v_mul_f32_e32 v128, v3, v2
	v_fma_f32 v129, -v1, v128, v3
	v_fmac_f32_e32 v128, v129, v2
	v_fma_f32 v1, -v1, v128, v3
	v_div_fmas_f32 v1, v1, v2, v128
	v_lshlrev_b32_e32 v129, 4, v236
	v_div_fixup_f32 v128, v1, v0, v234
	v_lshl_add_u64 v[136:137], s[4:5], 0, v[204:205]
	v_lshlrev_b32_e32 v204, 12, v235
	s_waitcnt vmcnt(0)
	v_pk_mul_f32 v[124:125], v[124:125], v[162:163]
	v_pk_mul_f32 v[126:127], v[126:127], v[160:161]
	v_pk_mul_f32 v[124:125], v[124:125], v[130:131] op_sel_hi:[1, 0]
	v_pk_mul_f32 v[126:127], v[126:127], v[130:131] op_sel_hi:[1, 0]
	v_pk_mul_f32 v[0:1], v[120:121], v[160:161]
	v_cvt_pk_bf16_f32 v126, v126, v127
	v_cvt_pk_bf16_f32 v127, v124, v125
	v_lshl_add_u64 v[124:125], v[136:137], 0, v[204:205]
	v_pk_mul_f32 v[2:3], v[122:123], v[162:163]
	v_pk_mul_f32 v[0:1], v[0:1], v[128:129] op_sel_hi:[1, 0]
	v_or_b32_e32 v204, 0x10000, v204
	global_store_dwordx2 v[124:125], v[126:127], off
	v_pk_mul_f32 v[2:3], v[2:3], v[128:129] op_sel_hi:[1, 0]
	v_cvt_pk_bf16_f32 v120, v0, v1
	v_lshl_add_u64 v[0:1], v[136:137], 0, v[204:205]
	v_cvt_pk_bf16_f32 v121, v2, v3
	global_store_dwordx2 v[0:1], v[120:121], off
	v_pk_mul_f32 v[2:3], v[118:119], v[166:167]
	v_pk_mul_f32 v[116:117], v[116:117], v[164:165]
	v_pk_mul_f32 v[2:3], v[2:3], v[130:131] op_sel_hi:[1, 0]
	v_pk_mul_f32 v[116:117], v[116:117], v[130:131] op_sel_hi:[1, 0]
	v_pk_mul_f32 v[112:113], v[112:113], v[164:165]
	v_cvt_pk_bf16_f32 v116, v116, v117
	v_cvt_pk_bf16_f32 v117, v2, v3
	v_pk_mul_f32 v[2:3], v[114:115], v[166:167]
	v_pk_mul_f32 v[112:113], v[112:113], v[128:129] op_sel_hi:[1, 0]
	global_store_dwordx2 v[124:125], v[116:117], off offset:32
	v_pk_mul_f32 v[2:3], v[2:3], v[128:129] op_sel_hi:[1, 0]
	v_cvt_pk_bf16_f32 v112, v112, v113
	s_nop 0
	v_cvt_pk_bf16_f32 v113, v2, v3
	global_store_dwordx2 v[0:1], v[112:113], off offset:32
	v_pk_mul_f32 v[2:3], v[110:111], v[170:171]
	v_pk_mul_f32 v[108:109], v[108:109], v[168:169]
	v_pk_mul_f32 v[2:3], v[130:131], v[2:3] op_sel_hi:[0, 1]
	v_pk_mul_f32 v[108:109], v[130:131], v[108:109] op_sel_hi:[0, 1]
	v_pk_mul_f32 v[104:105], v[104:105], v[168:169]
	v_cvt_pk_bf16_f32 v108, v108, v109
	v_cvt_pk_bf16_f32 v109, v2, v3
	v_pk_mul_f32 v[2:3], v[106:107], v[170:171]
	v_pk_mul_f32 v[104:105], v[128:129], v[104:105] op_sel_hi:[0, 1]
	global_store_dwordx2 v[124:125], v[108:109], off offset:64
	v_pk_mul_f32 v[2:3], v[128:129], v[2:3] op_sel_hi:[0, 1]
	v_cvt_pk_bf16_f32 v104, v104, v105
	v_cvt_pk_bf16_f32 v105, v2, v3
	global_store_dwordx2 v[0:1], v[104:105], off offset:64
	v_pk_mul_f32 v[2:3], v[102:103], v[174:175]
	v_pk_mul_f32 v[100:101], v[100:101], v[172:173]
	v_pk_mul_f32 v[2:3], v[130:131], v[2:3] op_sel_hi:[0, 1]
	v_pk_mul_f32 v[100:101], v[130:131], v[100:101] op_sel_hi:[0, 1]
	v_pk_mul_f32 v[96:97], v[96:97], v[172:173]
	v_cvt_pk_bf16_f32 v100, v100, v101
	v_cvt_pk_bf16_f32 v101, v2, v3
	v_pk_mul_f32 v[2:3], v[98:99], v[174:175]
	v_pk_mul_f32 v[96:97], v[128:129], v[96:97] op_sel_hi:[0, 1]
	global_store_dwordx2 v[124:125], v[100:101], off offset:96
	v_pk_mul_f32 v[2:3], v[128:129], v[2:3] op_sel_hi:[0, 1]
	v_cvt_pk_bf16_f32 v96, v96, v97
	v_cvt_pk_bf16_f32 v97, v2, v3
	global_store_dwordx2 v[0:1], v[96:97], off offset:96
	v_pk_mul_f32 v[2:3], v[94:95], v[178:179]
	v_pk_mul_f32 v[92:93], v[92:93], v[176:177]
	v_pk_mul_f32 v[2:3], v[130:131], v[2:3] op_sel_hi:[0, 1]
	v_pk_mul_f32 v[92:93], v[130:131], v[92:93] op_sel_hi:[0, 1]
	v_pk_mul_f32 v[88:89], v[88:89], v[176:177]
	v_cvt_pk_bf16_f32 v92, v92, v93
	v_cvt_pk_bf16_f32 v93, v2, v3
	v_pk_mul_f32 v[2:3], v[90:91], v[178:179]
	v_pk_mul_f32 v[88:89], v[128:129], v[88:89] op_sel_hi:[0, 1]
	global_store_dwordx2 v[124:125], v[92:93], off offset:128
	v_pk_mul_f32 v[2:3], v[128:129], v[2:3] op_sel_hi:[0, 1]
	v_cvt_pk_bf16_f32 v88, v88, v89
	v_cvt_pk_bf16_f32 v89, v2, v3
	global_store_dwordx2 v[0:1], v[88:89], off offset:128
	v_pk_mul_f32 v[2:3], v[86:87], v[182:183]
	v_pk_mul_f32 v[84:85], v[84:85], v[180:181]
	v_pk_mul_f32 v[2:3], v[130:131], v[2:3] op_sel_hi:[0, 1]
	v_pk_mul_f32 v[84:85], v[130:131], v[84:85] op_sel_hi:[0, 1]
	v_pk_mul_f32 v[80:81], v[80:81], v[180:181]
	v_cvt_pk_bf16_f32 v84, v84, v85
	v_cvt_pk_bf16_f32 v85, v2, v3
	v_pk_mul_f32 v[2:3], v[82:83], v[182:183]
	v_pk_mul_f32 v[80:81], v[128:129], v[80:81] op_sel_hi:[0, 1]
	global_store_dwordx2 v[124:125], v[84:85], off offset:160
	v_pk_mul_f32 v[2:3], v[128:129], v[2:3] op_sel_hi:[0, 1]
	v_cvt_pk_bf16_f32 v80, v80, v81
	v_cvt_pk_bf16_f32 v81, v2, v3
	global_store_dwordx2 v[0:1], v[80:81], off offset:160
	v_pk_mul_f32 v[2:3], v[78:79], v[186:187]
	v_pk_mul_f32 v[76:77], v[76:77], v[184:185]
	v_pk_mul_f32 v[2:3], v[130:131], v[2:3] op_sel_hi:[0, 1]
; __device__ __forceinline__ unsigned cvt_pk_bf16(float lo, float hi) { unsigned r; asm volatile("v_cvt_pk_bf16_f32 %0, %1, %2" : "=v"(r) : "v"(lo), "v"(hi)); return r; }
; template <int DV, int NMAP> ...
;     ...
;             for (int db = 0; db < DV / 16; ++db) { const f32x4 g = *(const f32x4*)(subg + 16 * db + 4 * fq);
; #pragma unroll
;                 for (int qb = 0; qb < 2; ++qb) { const f32x4 v = o[db][qb] * g * ss[qb]; v2u w; w.x = pg8::cvt_pk_bf16(v[0], v[1]); w.y = pg8::cvt_pk_bf16(v[2], v[3]);
;                     *(v2u*)(O + (size_t)(q0w + 16 * qb + fr) * DM + vrow0 + 16 * db + 4 * fq) = w; } }
	v_pk_mul_f32 v[76:77], v[130:131], v[76:77] op_sel_hi:[0, 1]
	v_pk_mul_f32 v[72:73], v[72:73], v[184:185]
	v_cvt_pk_bf16_f32 v76, v76, v77
	v_cvt_pk_bf16_f32 v77, v2, v3
	v_pk_mul_f32 v[2:3], v[74:75], v[186:187]
	v_pk_mul_f32 v[72:73], v[128:129], v[72:73] op_sel_hi:[0, 1]
	global_store_dwordx2 v[124:125], v[76:77], off offset:192
	v_pk_mul_f32 v[2:3], v[128:129], v[2:3] op_sel_hi:[0, 1]
	v_cvt_pk_bf16_f32 v72, v72, v73
	v_cvt_pk_bf16_f32 v73, v2, v3
	global_store_dwordx2 v[0:1], v[72:73], off offset:192
	v_pk_mul_f32 v[2:3], v[70:71], v[190:191]
	v_pk_mul_f32 v[68:69], v[68:69], v[188:189]
	v_pk_mul_f32 v[2:3], v[130:131], v[2:3] op_sel_hi:[0, 1]
	v_pk_mul_f32 v[68:69], v[130:131], v[68:69] op_sel_hi:[0, 1]
	v_pk_mul_f32 v[64:65], v[64:65], v[188:189]
	v_cvt_pk_bf16_f32 v68, v68, v69
	v_cvt_pk_bf16_f32 v69, v2, v3
	v_pk_mul_f32 v[2:3], v[66:67], v[190:191]
	v_pk_mul_f32 v[64:65], v[128:129], v[64:65] op_sel_hi:[0, 1]
	global_store_dwordx2 v[124:125], v[68:69], off offset:224
	v_pk_mul_f32 v[2:3], v[128:129], v[2:3] op_sel_hi:[0, 1]
	v_cvt_pk_bf16_f32 v64, v64, v65
	v_cvt_pk_bf16_f32 v65, v2, v3
	global_store_dwordx2 v[0:1], v[64:65], off offset:224
	v_pk_mul_f32 v[2:3], v[62:63], v[194:195]
	v_pk_mul_f32 v[60:61], v[60:61], v[192:193]
	v_pk_mul_f32 v[2:3], v[130:131], v[2:3] op_sel_hi:[0, 1]
	v_pk_mul_f32 v[60:61], v[130:131], v[60:61] op_sel_hi:[0, 1]
	v_pk_mul_f32 v[56:57], v[56:57], v[192:193]
	v_cvt_pk_bf16_f32 v60, v60, v61
	v_cvt_pk_bf16_f32 v61, v2, v3
	v_pk_mul_f32 v[2:3], v[58:59], v[194:195]
	v_pk_mul_f32 v[56:57], v[128:129], v[56:57] op_sel_hi:[0, 1]
	global_store_dwordx2 v[124:125], v[60:61], off offset:256
	v_pk_mul_f32 v[2:3], v[128:129], v[2:3] op_sel_hi:[0, 1]
	v_cvt_pk_bf16_f32 v56, v56, v57
	v_cvt_pk_bf16_f32 v57, v2, v3
	global_store_dwordx2 v[0:1], v[56:57], off offset:256
	v_pk_mul_f32 v[2:3], v[54:55], v[198:199]
	v_pk_mul_f32 v[52:53], v[52:53], v[196:197]
	v_pk_mul_f32 v[2:3], v[130:131], v[2:3] op_sel_hi:[0, 1]
	v_pk_mul_f32 v[52:53], v[130:131], v[52:53] op_sel_hi:[0, 1]
	v_pk_mul_f32 v[48:49], v[48:49], v[196:197]
	v_cvt_pk_bf16_f32 v52, v52, v53
	v_cvt_pk_bf16_f32 v53, v2, v3
	v_pk_mul_f32 v[2:3], v[50:51], v[198:199]
	v_pk_mul_f32 v[48:49], v[128:129], v[48:49] op_sel_hi:[0, 1]
	global_store_dwordx2 v[124:125], v[52:53], off offset:288
	v_pk_mul_f32 v[2:3], v[128:129], v[2:3] op_sel_hi:[0, 1]
	v_cvt_pk_bf16_f32 v48, v48, v49
	v_cvt_pk_bf16_f32 v49, v2, v3
	global_store_dwordx2 v[0:1], v[48:49], off offset:288
	v_pk_mul_f32 v[2:3], v[46:47], v[202:203]
	v_pk_mul_f32 v[44:45], v[44:45], v[200:201]
	v_pk_mul_f32 v[2:3], v[130:131], v[2:3] op_sel_hi:[0, 1]
	v_pk_mul_f32 v[44:45], v[130:131], v[44:45] op_sel_hi:[0, 1]
	v_pk_mul_f32 v[40:41], v[40:41], v[200:201]
	v_cvt_pk_bf16_f32 v44, v44, v45
	v_cvt_pk_bf16_f32 v45, v2, v3
	v_pk_mul_f32 v[2:3], v[42:43], v[202:203]
	v_pk_mul_f32 v[40:41], v[128:129], v[40:41] op_sel_hi:[0, 1]
	global_store_dwordx2 v[124:125], v[44:45], off offset:320
	v_pk_mul_f32 v[2:3], v[128:129], v[2:3] op_sel_hi:[0, 1]
	v_cvt_pk_bf16_f32 v40, v40, v41
	v_cvt_pk_bf16_f32 v41, v2, v3
	global_store_dwordx2 v[0:1], v[40:41], off offset:320
	v_pk_mul_f32 v[2:3], v[38:39], v[150:151]
	v_pk_mul_f32 v[36:37], v[36:37], v[148:149]
	v_pk_mul_f32 v[2:3], v[130:131], v[2:3] op_sel_hi:[0, 1]
	v_pk_mul_f32 v[36:37], v[130:131], v[36:37] op_sel_hi:[0, 1]
	v_pk_mul_f32 v[32:33], v[32:33], v[148:149]
	v_cvt_pk_bf16_f32 v36, v36, v37
	v_cvt_pk_bf16_f32 v37, v2, v3
	v_pk_mul_f32 v[2:3], v[34:35], v[150:151]
	v_pk_mul_f32 v[32:33], v[128:129], v[32:33] op_sel_hi:[0, 1]
	global_store_dwordx2 v[124:125], v[36:37], off offset:352
	v_pk_mul_f32 v[2:3], v[128:129], v[2:3] op_sel_hi:[0, 1]
	v_cvt_pk_bf16_f32 v32, v32, v33
	v_cvt_pk_bf16_f32 v33, v2, v3
	global_store_dwordx2 v[0:1], v[32:33], off offset:352
	v_pk_mul_f32 v[2:3], v[30:31], v[154:155]
	v_pk_mul_f32 v[28:29], v[28:29], v[152:153]
	v_pk_mul_f32 v[2:3], v[130:131], v[2:3] op_sel_hi:[0, 1]
	v_pk_mul_f32 v[28:29], v[130:131], v[28:29] op_sel_hi:[0, 1]
	v_pk_mul_f32 v[24:25], v[24:25], v[152:153]
	v_cvt_pk_bf16_f32 v28, v28, v29
	v_cvt_pk_bf16_f32 v29, v2, v3
	v_pk_mul_f32 v[2:3], v[26:27], v[154:155]
	v_pk_mul_f32 v[24:25], v[128:129], v[24:25] op_sel_hi:[0, 1]
	global_store_dwordx2 v[124:125], v[28:29], off offset:384
	v_pk_mul_f32 v[2:3], v[128:129], v[2:3] op_sel_hi:[0, 1]
	v_cvt_pk_bf16_f32 v24, v24, v25
	v_cvt_pk_bf16_f32 v25, v2, v3
	global_store_dwordx2 v[0:1], v[24:25], off offset:384
	v_pk_mul_f32 v[20:21], v[20:21], v[240:241]
	v_pk_mul_f32 v[2:3], v[22:23], v[242:243]
	v_pk_mul_f32 v[20:21], v[130:131], v[20:21] op_sel_hi:[0, 1]
	v_pk_mul_f32 v[2:3], v[130:131], v[2:3] op_sel_hi:[0, 1]
	v_cvt_pk_bf16_f32 v20, v20, v21
	v_cvt_pk_bf16_f32 v21, v2, v3
	global_store_dwordx2 v[124:125], v[20:21], off offset:416
	v_pk_mul_f32 v[20:21], v[134:135], v[240:241]
	v_pk_mul_f32 v[2:3], v[132:133], v[242:243]
	v_pk_mul_f32 v[20:21], v[128:129], v[20:21] op_sel_hi:[0, 1]
	v_pk_mul_f32 v[2:3], v[128:129], v[2:3] op_sel_hi:[0, 1]
	v_cvt_pk_bf16_f32 v20, v20, v21
	v_cvt_pk_bf16_f32 v21, v2, v3
	global_store_dwordx2 v[0:1], v[20:21], off offset:416
	v_pk_mul_f32 v[2:3], v[12:13], v[246:247]
	v_pk_mul_f32 v[12:13], v[14:15], v[244:245]
	v_pk_mul_f32 v[2:3], v[130:131], v[2:3] op_sel_hi:[0, 1]
	v_pk_mul_f32 v[12:13], v[130:131], v[12:13] op_sel_hi:[0, 1]
	v_pk_mul_f32 v[8:9], v[8:9], v[244:245]
	v_cvt_pk_bf16_f32 v12, v12, v13
	v_cvt_pk_bf16_f32 v13, v2, v3
	v_pk_mul_f32 v[2:3], v[10:11], v[246:247]
	v_pk_mul_f32 v[8:9], v[128:129], v[8:9] op_sel_hi:[0, 1]
	global_store_dwordx2 v[124:125], v[12:13], off offset:448
	v_pk_mul_f32 v[2:3], v[128:129], v[2:3] op_sel_hi:[0, 1]
	v_cvt_pk_bf16_f32 v8, v8, v9
	v_cvt_pk_bf16_f32 v9, v2, v3
	global_store_dwordx2 v[0:1], v[8:9], off offset:448
	v_pk_mul_f32 v[4:5], v[4:5], v[248:249]
	v_pk_mul_f32 v[2:3], v[6:7], v[250:251]
	v_pk_mul_f32 v[4:5], v[130:131], v[4:5] op_sel_hi:[0, 1]
	v_pk_mul_f32 v[2:3], v[130:131], v[2:3] op_sel_hi:[0, 1]
	v_cvt_pk_bf16_f32 v4, v4, v5
	v_cvt_pk_bf16_f32 v5, v2, v3
	global_store_dwordx2 v[124:125], v[4:5], off offset:480
	v_pk_mul_f32 v[4:5], v[18:19], v[248:249]
	v_pk_mul_f32 v[2:3], v[16:17], v[250:251]
	v_pk_mul_f32 v[4:5], v[128:129], v[4:5] op_sel_hi:[0, 1]
	v_pk_mul_f32 v[2:3], v[128:129], v[2:3] op_sel_hi:[0, 1]
	v_cvt_pk_bf16_f32 v4, v4, v5
	v_cvt_pk_bf16_f32 v5, v2, v3
	global_store_dwordx2 v[0:1], v[4:5], off offset:480
	s_branch .LBB0_297
